# combined: early first X-pass tile loads + MoBA Q rows from registers + batched block-sum table staging
# speedup vs baseline: 1.0046x; 1.0034x over previous
; #define P2_STAGE_KM(tab_, bh_) do { for (int e = tid; e < 1024; e += NTHREADS) km[(tab_) * 1024 + e] = kmp[(size_t)(bh_) * 1024 + e] + kmp[(size_t)(64 + (bh_)) * 1024 + e]; } while (0)
; __global__ void __launch_bounds__(NTHREADS) fwd_megakernel(Params P) {
;     ...
;         for (int rep = 0; rep < 2; ++rep) {
;             if (rep == 0 || NREP(2) == 2) {
;                 __syncthreads();
;                 { int k = 0; for (int it = bid; it < 512 && k < 2; it += G, ++k) { P2_DECODE(it); (void)sub; P2_STAGE_KM(k, bh); } }
;                 __syncthreads();
.LBB0_499:
	s_or_b64 exec, exec, s[0:1]
	s_cmpk_lt_i32 s3, 0x200
	s_cselect_b64 s[4:5], -1, 0
	v_mov_b32_e32 v184, v234
	s_movk_i32 s0, 0x400
	v_writelane_b32 v255, s4, 1
	s_waitcnt lgkmcnt(0)
	s_barrier
	v_writelane_b32 v255, s5, 2
	v_readfirstlane_b32 s30, v184
	v_cmp_gt_i32_e64 s[6:7], s0, v184
	s_and_b64 vcc, exec, s[4:5]
	v_lshlrev_b32_e32 v187, 2, v184
	s_barrier
	s_cbranch_vccz .LBB0_517
	s_and_b32 s0, s3, 7
	s_lshl_b32 s0, s0, 3
	s_lshr_b32 s1, s3, 6
	s_add_i32 s0, s0, s1
	s_lshl_b32 s0, s0, 12
	s_add_u32 s20, s62, s0
	s_addc_u32 s21, s63, 0
	v_lshlrev_b32_e32 v0, 2, v184
	global_load_dword v8, v0, s[20:21]
	global_load_dword v9, v0, s[20:21] offset:2048
	s_add_u32 s54, s20, 0x40000
	s_addc_u32 s55, s21, 0
	global_load_dword v10, v0, s[54:55]
	global_load_dword v11, v0, s[54:55] offset:2048
	s_add_u32 s20, s20, 0x4000
	s_addc_u32 s21, s21, 0
	s_add_u32 s54, s54, 0x4000
	s_addc_u32 s55, s55, 0
	global_load_dword v12, v0, s[20:21]
	global_load_dword v13, v0, s[20:21] offset:2048
	global_load_dword v14, v0, s[54:55]
	global_load_dword v15, v0, s[54:55] offset:2048
	v_add_u32_e32 v1, 0x12000, v0
	s_waitcnt vmcnt(0)
	v_add_f32_e32 v8, v8, v10
	v_add_f32_e32 v9, v9, v11
	v_add_f32_e32 v12, v12, v14
	v_add_f32_e32 v13, v13, v15
	ds_write_b32 v1, v8
	ds_write_b32 v1, v9 offset:2048
	ds_write_b32 v1, v12 offset:4096
	ds_write_b32 v1, v13 offset:6144
